# phase 4 (block-diagonal LoRA GEMM): only the two K-tiles that hold a tile's non-zero weight block are run (exact zeros skipped)
# baseline (speedup 1.0000x reference)
.LBB0_118:
	s_andn2_b64 vcc, exec, s[28:29]
	s_cbranch_vccnz .LBB0_225
	v_bfe_i32 v3, v15, 27, 1
	v_lshlrev_b32_e32 v1, 4, v15
	v_lshrrev_b32_e32 v3, 22, v3
	v_add_u32_e32 v3, v1, v3
	v_and_b32_e32 v3, 0xfffffc00, v3
	v_sub_u32_e32 v3, v1, v3
	v_lshrrev_b32_e32 v4, 4, v3
	v_ashrrev_i32_e32 v2, 31, v15
	v_bitop3_b32 v3, v4, v3, 32 bitop3:0x6c
	v_lshrrev_b32_e32 v2, 26, v2
	v_ashrrev_i32_e32 v5, 31, v3
	v_add_u32_e32 v2, v15, v2
	v_lshrrev_b32_e32 v5, 26, v5
	v_ashrrev_i32_e32 v2, 6, v2
	v_add_u32_e32 v5, v3, v5
	v_lshlrev_b32_e32 v4, 3, v2
	v_ashrrev_i32_e32 v6, 6, v5
	v_and_b32_e32 v5, 0xc0, v5
	v_and_b32_e32 v4, -16, v4
	v_lshlrev_b32_e32 v2, 5, v2
	v_sub_u32_e32 v3, v3, v5
	v_mov_b32_e32 v8, 1
	v_add_u32_e32 v4, v6, v4
	v_and_b32_e32 v2, 32, v2
	v_ashrrev_i16_sdwa v3, v8, sext(v3) dst_sel:DWORD dst_unused:UNUSED_PAD src0_sel:DWORD src1_sel:BYTE_0
	v_add_u32_sdwa v2, v2, sext(v3) dst_sel:DWORD dst_unused:UNUSED_PAD src0_sel:DWORD src1_sel:WORD_0
	v_lshlrev_b32_e32 v3, 1, v4
	v_lshrrev_b32_e32 v5, 2, v4
	v_and_b32_e32 v6, 3, v6
	s_mov_b32 s3, 0x7fffffe0
	v_and_b32_e32 v3, 24, v3
	v_and_b32_e32 v5, 4, v5
	v_and_or_b32 v6, v4, s3, v6
	v_or3_b32 v3, v6, v5, v3
	v_lshlrev_b32_e32 v6, 2, v4
	v_and_b32_e32 v5, 0xffffffc0, v4
	v_and_b32_e32 v6, 60, v6
	v_bfe_u32 v7, v4, 4, 2
	v_or3_b32 v5, v6, v5, v7
	v_cndmask_b32_e64 v4, v5, v4, s[40:41]
	v_mul_lo_u32 v4, v4, s10
	v_mul_lo_u32 v3, v3, s10
	v_add_u32_e32 v1, 0x2000, v1
	v_add_lshl_u32 v164, v4, v2, 1
	v_add_lshl_u32 v166, v3, v2, 1
	v_ashrrev_i32_e32 v2, 31, v1
	v_lshrrev_b32_e32 v2, 22, v2
	v_add_u32_e32 v2, v1, v2
	v_ashrrev_i32_e32 v2, 10, v2
	v_mul_i32_i24_e32 v3, 0x400, v2
	v_sub_u32_e32 v1, v1, v3
	v_lshrrev_b32_e32 v3, 4, v1
	v_bitop3_b32 v1, v3, v1, 32 bitop3:0x6c
	v_ashrrev_i32_e32 v4, 31, v1
	v_lshrrev_b32_e32 v4, 26, v4
	v_lshlrev_b32_e32 v3, 3, v2
	v_add_u32_e32 v4, v1, v4
	v_and_b32_e32 v3, -16, v3
	v_ashrrev_i32_e32 v5, 6, v4
	v_add_u32_e32 v3, v5, v3
	v_and_b32_e32 v5, 3, v5
	s_lshl_b32 s96, s10, 8
	v_and_or_b32 v5, v3, s3, v5
	s_lshl_b64 s[70:71], s[96:97], 1
	s_ashr_i32 s3, s69, 31
	s_mul_i32 s3, s70, s3
	s_mul_hi_u32 s9, s70, s69
	s_add_i32 s3, s9, s3
	s_bfe_u32 s9, s10, 0x10017
	s_mul_i32 s28, s9, s69
	s_add_i32 s30, s3, s28
	s_ashr_i32 s3, s54, 31
	v_and_b32_e32 v4, 0xc0, v4
	s_mul_i32 s3, s70, s3
	s_mul_hi_u32 s28, s70, s54
	s_ashr_i32 s11, s25, 6
	v_lshlrev_b32_e32 v2, 5, v2
	v_sub_u32_e32 v1, v1, v4
	s_add_i32 s3, s28, s3
	s_mul_i32 s9, s9, s54
	v_and_b32_e32 v2, 32, v2
	v_ashrrev_i16_sdwa v1, v8, sext(v1) dst_sel:DWORD dst_unused:UNUSED_PAD src0_sel:DWORD src1_sel:BYTE_0
	s_ashr_i32 s76, s25, 8
	s_lshl_b32 s77, s11, 10
	s_add_i32 s3, s3, s9
	s_mul_i32 s9, s70, s54
	v_add_u32_sdwa v1, v2, sext(v1) dst_sel:DWORD dst_unused:UNUSED_PAD src0_sel:DWORD src1_sel:WORD_0
	v_lshlrev_b32_e32 v2, 1, v3
	v_lshrrev_b32_e32 v4, 2, v3
	s_add_u32 s88, s14, s9
	v_and_b32_e32 v2, 24, v2
	v_and_b32_e32 v4, 4, v4
	s_addc_u32 s89, s15, s3
	s_cmp_eq_u32 s87, 4
	s_cselect_b32 s101, 1, 0
	s_cmp_gt_u32 s54, 3
	s_cselect_b32 s94, 0x100, 0
	s_mul_i32 s94, s94, s101
	s_add_u32 s88, s88, s94
	s_addc_u32 s89, s89, 0
	s_add_i32 s3, s77, 0
	v_or3_b32 v2, v5, v4, v2
	s_add_i32 m0, s3, 0x10000
	v_mul_lo_u32 v2, v2, s10
	global_load_lds_dwordx4 v166, s[88:89]
	s_add_i32 m0, s3, 0x12000
	v_add_lshl_u32 v170, v2, v1, 1
	s_add_u32 s28, s88, s96
	v_lshlrev_b32_e32 v5, 2, v3
	global_load_lds_dwordx4 v170, s[88:89]
	s_addc_u32 s29, s89, 0
	s_add_i32 m0, s3, 0x14000
	v_and_b32_e32 v4, 0xffffffc0, v3
	v_and_b32_e32 v5, 60, v5
	v_bfe_u32 v6, v3, 4, 2
	s_mul_i32 s31, s70, s69
	global_load_lds_dwordx4 v166, s[28:29]
	s_add_i32 m0, s3, 0x16000
	v_or3_b32 v4, v5, v4, v6
	s_add_u32 s38, s12, s31
	v_cndmask_b32_e64 v3, v4, v3, s[40:41]
	s_addc_u32 s39, s13, s30
	s_add_u32 s38, s38, s94
	s_addc_u32 s39, s39, 0
	s_add_i32 s78, s3, 0x2000
	v_mul_lo_u32 v3, v3, s10
	global_load_lds_dwordx4 v170, s[28:29]
	s_mov_b32 m0, s3
	s_add_u32 s30, s38, s96
	v_add_lshl_u32 v168, v3, v1, 1
	global_load_lds_dwordx4 v164, s[38:39]
	s_mov_b32 m0, s78
	s_addc_u32 s31, s39, 0
	s_add_i32 s9, s3, 0x4000
	global_load_lds_dwordx4 v168, s[38:39]
	s_mov_b32 m0, s9
	s_add_i32 s86, s3, 0x6000
	global_load_lds_dwordx4 v164, s[30:31]
	s_mov_b32 m0, s86
	v_writelane_b32 v255, s46, 5
	global_load_lds_dwordx4 v168, s[30:31]
	s_nop 0
	v_writelane_b32 v255, s47, 6
	v_writelane_b32 v255, s44, 7
	v_mov_b32_e32 v167, v0
	v_mov_b32_e32 v171, v0
	v_writelane_b32 v255, s45, 8
	v_writelane_b32 v255, s42, 9
	v_mov_b32_e32 v165, v0
	v_mov_b32_e32 v169, v0
	s_cmp_eq_u32 s76, 1
	v_writelane_b32 v255, s43, 10
	v_lshl_add_u64 v[10:11], s[88:89], 0, v[166:167]
	v_lshl_add_u64 v[6:7], s[88:89], 0, v[170:171]
	v_lshl_add_u64 v[4:5], s[28:29], 0, v[166:167]
	v_lshl_add_u64 v[2:3], s[28:29], 0, v[170:171]
	v_lshl_add_u64 v[8:9], s[38:39], 0, v[164:165]
	s_cselect_b64 s[28:29], -1, 0
	s_cmp_lg_u32 s76, 1
	v_lshl_add_u64 v[12:13], s[38:39], 0, v[168:169]
	s_cbranch_scc1 .LBB0_121
	s_barrier
.LBB0_121:
	s_add_i32 m0, s3, 0x18000
	v_lshl_add_u64 v[10:11], v[10:11], 0, s[4:5]
	s_waitcnt vmcnt(2)
	s_barrier
	global_load_lds_dwordx4 v[10:11], off
	v_lshl_add_u64 v[6:7], v[6:7], 0, s[4:5]
	s_add_i32 m0, s3, 0x1a000
	s_add_i32 s80, s3, 0x8000
	global_load_lds_dwordx4 v[6:7], off
	v_lshl_add_u64 v[6:7], v[8:9], 0, s[4:5]
	s_mov_b32 m0, s80
	s_add_i32 s84, s3, 0xa000
	global_load_lds_dwordx4 v[6:7], off
	v_lshl_add_u64 v[6:7], v[12:13], 0, s[4:5]
	s_mov_b32 m0, s84
	v_lshl_add_u64 v[4:5], v[4:5], 0, s[4:5]
	global_load_lds_dwordx4 v[6:7], off
	s_add_i32 m0, s3, 0x1c000
	v_lshl_add_u64 v[2:3], v[2:3], 0, s[4:5]
	global_load_lds_dwordx4 v[4:5], off
	s_add_i32 m0, s3, 0x1e000
	s_lshl_b32 s11, s11, 5
	global_load_lds_dwordx4 v[2:3], off
	v_lshrrev_b32_e32 v2, 1, v15
	v_and_b32_e32 v2, 24, v2
	s_and_b32 s34, s11, 0x60
	v_and_b32_e32 v1, 15, v15
	v_lshlrev_b32_e32 v3, 1, v2
	v_or_b32_e32 v172, s34, v2
	v_rcp_iflag_f32_e32 v2, v14
	v_lshlrev_b32_e32 v241, 2, v1
	s_lshr_b32 s83, s10, 6
	s_cmp_eq_u32 s101, 1
	s_cselect_b32 s83, 2, s83
	v_lshl_or_b32 v3, v1, 6, v3
	v_and_b32_e32 v4, 32, v241
	s_mov_b32 s100, 0x14000
	s_mov_b32 s11, 7
	s_cmp_eq_u32 s81, 0
	s_cbranch_scc1 .Lfl_remap
	s_cmp_eq_u32 s81, 3
	s_cbranch_scc1 .Lfl_remap
	s_branch .Lfl_noremap

.LBB0_130:
	s_cmp_gt_u32 s68, 3
	s_cselect_b32 s94, 0x100, 0
	s_mul_i32 s94, s94, s101
	s_cmp_eq_u64 s[42:43], 0
	s_cselect_b32 s94, s94, 0
	s_add_u32 s92, s92, s94
	s_addc_u32 s93, s93, 0
	s_add_u32 s98, s98, s94
	s_addc_u32 s99, s99, 0
	s_add_u32 s38, s38, 0x80
	s_addc_u32 s39, s39, 0
	s_add_u32 s56, s88, 0x100
	s_addc_u32 s57, s89, 0
	s_mov_b32 s44, 0
	v_mov_b64_e32 v[2:3], 0
	v_mov_b64_e32 v[4:5], 0
	v_mov_b64_e32 v[6:7], 0
	v_mov_b64_e32 v[8:9], 0
	v_mov_b64_e32 v[10:11], 0
	v_mov_b64_e32 v[12:13], 0
	v_mov_b64_e32 v[14:15], 0
	v_mov_b64_e32 v[16:17], 0
	v_mov_b64_e32 v[18:19], 0
	v_mov_b64_e32 v[20:21], 0
	v_mov_b64_e32 v[22:23], 0
	v_mov_b64_e32 v[24:25], 0
	v_mov_b64_e32 v[26:27], 0
	v_mov_b64_e32 v[28:29], 0
	v_mov_b64_e32 v[30:31], 0
	v_mov_b64_e32 v[32:33], 0
	v_mov_b64_e32 v[34:35], 0
	v_mov_b64_e32 v[36:37], 0
	v_mov_b64_e32 v[38:39], 0
	v_mov_b64_e32 v[40:41], 0
	v_mov_b64_e32 v[42:43], 0
	v_mov_b64_e32 v[44:45], 0
	v_mov_b64_e32 v[46:47], 0
	v_mov_b64_e32 v[48:49], 0
	v_mov_b64_e32 v[50:51], 0
	v_mov_b64_e32 v[52:53], 0
	v_mov_b64_e32 v[54:55], 0
	v_mov_b64_e32 v[56:57], 0
	v_mov_b64_e32 v[58:59], 0
	v_mov_b64_e32 v[60:61], 0
	v_mov_b64_e32 v[62:63], 0
	v_mov_b64_e32 v[64:65], 0
	v_mov_b64_e32 v[66:67], 0
	v_mov_b64_e32 v[68:69], 0
	v_mov_b64_e32 v[70:71], 0
	v_mov_b64_e32 v[72:73], 0
	v_mov_b64_e32 v[74:75], 0
	v_mov_b64_e32 v[76:77], 0
	v_mov_b64_e32 v[78:79], 0
	v_mov_b64_e32 v[80:81], 0
	v_mov_b64_e32 v[82:83], 0
	v_mov_b64_e32 v[84:85], 0
	v_mov_b64_e32 v[86:87], 0
	v_mov_b64_e32 v[88:89], 0
	v_mov_b64_e32 v[90:91], 0
	v_mov_b64_e32 v[92:93], 0
	v_mov_b64_e32 v[94:95], 0
	v_mov_b64_e32 v[96:97], 0
	v_mov_b64_e32 v[98:99], 0
	v_mov_b64_e32 v[100:101], 0
	v_mov_b64_e32 v[102:103], 0
	v_mov_b64_e32 v[104:105], 0
	v_mov_b64_e32 v[106:107], 0
	v_mov_b64_e32 v[108:109], 0
	v_mov_b64_e32 v[110:111], 0
	v_mov_b64_e32 v[112:113], 0
	v_mov_b64_e32 v[114:115], 0
	v_mov_b64_e32 v[116:117], 0
	v_mov_b64_e32 v[118:119], 0
	v_mov_b64_e32 v[120:121], 0
	v_mov_b64_e32 v[122:123], 0
	v_mov_b64_e32 v[124:125], 0
	v_mov_b64_e32 v[126:127], 0
	v_mov_b64_e32 v[128:129], 0
